# v50 + prologue de-serialisation: in all 12 GEMM phase prologues the K-tile-1 LDS-DMA group (6 loads) is issued before the wait+barrier on the first group (vmcnt 2 -> 8 after the issue)
# speedup vs baseline: 1.0003x; 1.0003x over previous
.LBB0_291:
	s_lshl_b32 s11, s11, 11
	s_lshl_b32 s8, s8, 5
	s_or_b32 s15, s11, s12
	s_lshl_b32 s24, s9, 6
	s_lshl_b32 s11, s9, 13
	s_and_b32 s25, s8, 0x60
	s_mov_b64 s[8:9], 0x80
	s_add_i32 m0, s16, 0x18000
	v_lshl_add_u64 v[8:9], v[8:9], 0, s[8:9]
	global_load_lds_dwordx4 v[8:9], off
	v_lshl_add_u64 v[6:7], v[6:7], 0, s[8:9]
	s_add_i32 m0, s16, 0x1a000
	s_add_i32 s28, s16, 0x8000
	s_add_i32 s29, s16, 0xa000
	global_load_lds_dwordx4 v[6:7], off
	v_lshl_add_u64 v[2:3], v[2:3], 0, s[8:9]
	s_mov_b32 m0, s28
	s_add_u32 s12, s36, 0x40080
	global_load_lds_dwordx4 v[2:3], off
	v_lshl_add_u64 v[2:3], v[4:5], 0, s[8:9]
	s_mov_b32 m0, s29
	s_addc_u32 s13, s37, 0
	global_load_lds_dwordx4 v[2:3], off
	s_add_i32 m0, s16, 0x1c000
	v_lshl_add_u64 v[2:3], s[12:13], 0, v[136:137]
	global_load_lds_dwordx4 v[2:3], off
	v_lshl_add_u64 v[2:3], s[12:13], 0, v[134:135]
	s_add_i32 m0, s16, 0x1e000
	s_cmpk_lt_u32 s10, 0x100
	global_load_lds_dwordx4 v[2:3], off
	s_waitcnt vmcnt(8)
	s_barrier
	v_lshlrev_b32_e32 v3, 2, v1
	v_lshl_or_b32 v2, v1, 6, v139
	v_and_b32_e32 v3, 32, v3
	s_waitcnt vmcnt(6)
	v_bitop3_b32 v2, v2, s11, v3 bitop3:0xde
	v_lshl_or_b32 v145, s25, 7, v140
	s_cselect_b64 s[10:11], -1, 0
	s_add_i32 s30, 0, 0x10000
	s_add_i32 s31, 0, 0x14000
	v_add_u32_e32 v146, s30, v145
	v_add_u32_e32 v147, s31, v145
	v_add_u32_e32 v148, 0, v2
	s_mov_b32 s34, 0
	s_barrier
	s_branch .LBB0_294

.LBB0_307:
	s_lshl_b32 s12, s12, 11
	s_or_b32 s15, s12, s13
	s_lshl_b32 s42, s11, 8
	s_add_u32 s24, s56, 0x5d00000
	s_addc_u32 s25, s57, 0
	s_lshl_b32 s8, s8, 5
	s_lshl_b32 s28, s9, 6
	s_lshl_b32 s11, s9, 13
	s_and_b32 s29, s8, 0x60
	s_mov_b64 s[8:9], 0x80
	s_add_i32 m0, s16, 0x18000
	v_lshl_add_u64 v[8:9], v[8:9], 0, s[8:9]
	global_load_lds_dwordx4 v[8:9], off
	v_lshl_add_u64 v[6:7], v[6:7], 0, s[8:9]
	s_add_i32 m0, s16, 0x1a000
	s_add_i32 s30, s16, 0x8000
	s_add_i32 s31, s16, 0xa000
	global_load_lds_dwordx4 v[6:7], off
	v_lshl_add_u64 v[2:3], v[2:3], 0, s[8:9]
	s_mov_b32 m0, s30
	s_add_u32 s12, s36, 0x1080
	global_load_lds_dwordx4 v[2:3], off
	v_lshl_add_u64 v[2:3], v[4:5], 0, s[8:9]
	s_mov_b32 m0, s31
	s_addc_u32 s13, s37, 0
	global_load_lds_dwordx4 v[2:3], off
	s_add_i32 m0, s16, 0x1c000
	v_lshl_add_u64 v[2:3], s[12:13], 0, v[136:137]
	global_load_lds_dwordx4 v[2:3], off
	v_lshl_add_u64 v[2:3], s[12:13], 0, v[134:135]
	s_add_i32 m0, s16, 0x1e000
	s_cmpk_lt_u32 s10, 0x100
	global_load_lds_dwordx4 v[2:3], off
	s_waitcnt vmcnt(8)
	s_barrier
	v_lshlrev_b32_e32 v3, 2, v1
	v_lshl_or_b32 v2, v1, 6, v139
	v_and_b32_e32 v3, 32, v3
	s_waitcnt vmcnt(6)
	v_bitop3_b32 v2, v2, s11, v3 bitop3:0xde
	v_lshl_or_b32 v139, s29, 7, v140
	s_cselect_b64 s[10:11], -1, 0
	s_add_i32 s33, 0, 0x10000
	s_add_i32 s34, 0, 0x14000
	v_add_u32_e32 v140, s33, v139
	v_add_u32_e32 v141, s34, v139
	v_add_u32_e32 v142, 0, v2
	s_mov_b32 s63, 0
	s_barrier
	s_branch .LBB0_310

.LBB0_378:
	s_lshl_b32 s10, s10, 5
	s_lshl_b32 s19, s11, 6
	s_lshl_b32 s13, s11, 13
	s_and_b32 s24, s10, 0x60
	s_mov_b64 s[10:11], 0x80
	s_add_i32 m0, s2, 0x18000
	v_lshl_add_u64 v[4:5], v[4:5], 0, s[10:11]
	global_load_lds_dwordx4 v[4:5], off
	s_add_i32 m0, s2, 0x1a000
	s_add_u32 s20, s56, 0x3540080
	v_lshl_add_u64 v[2:3], v[2:3], 0, s[10:11]
	s_addc_u32 s21, s57, 0
	s_add_i32 s25, s2, 0x8000
	global_load_lds_dwordx4 v[2:3], off
	v_lshl_add_u64 v[2:3], s[20:21], 0, v[136:137]
	s_mov_b32 m0, s25
	s_add_i32 s28, s2, 0xa000
	global_load_lds_dwordx4 v[2:3], off
	v_lshl_add_u64 v[2:3], s[20:21], 0, v[132:133]
	s_add_u32 s20, s42, 0x20080
	s_mov_b32 m0, s28
	s_addc_u32 s21, s43, 0
	global_load_lds_dwordx4 v[2:3], off
	s_add_i32 m0, s2, 0x1c000
	v_lshl_add_u64 v[2:3], s[20:21], 0, v[134:135]
	global_load_lds_dwordx4 v[2:3], off
	v_lshl_add_u64 v[2:3], s[20:21], 0, v[130:131]
	s_add_i32 m0, s2, 0x1e000
	s_cmpk_lt_u32 s12, 0x100
	global_load_lds_dwordx4 v[2:3], off
	s_waitcnt vmcnt(8)
	s_barrier
	v_lshlrev_b32_e32 v3, 2, v1
	v_lshl_or_b32 v2, v1, 6, v143
	v_and_b32_e32 v3, 32, v3
	v_bitop3_b32 v4, v2, s13, v3 bitop3:0xde
	v_lshlrev_b32_e32 v2, 7, v0
	v_and_b32_e32 v2, 0xc000, v2
	v_lshlrev_b32_e32 v3, 10, v9
	v_or3_b32 v2, v6, v2, v3
	v_add_u32_e32 v2, v2, v7
	v_mov_b32_e32 v3, v135
	v_lshl_add_u64 v[2:3], s[56:57], 0, v[2:3]
	s_mov_b64 s[20:21], 0x3560080
	v_lshl_or_b32 v5, s24, 7, v144
	s_waitcnt vmcnt(6)
	s_cselect_b64 s[12:13], -1, 0
	v_lshl_add_u64 v[138:139], v[2:3], 0, s[20:21]
	v_add3_u32 v2, v8, v6, v7
	v_mov_b32_e32 v3, v135
	s_add_i32 s31, 0, 0x10000
	s_add_i32 s34, 0, 0x14000
	s_add_i32 s62, 0, 0x18000
	s_add_i32 s64, 0, 0x1c000
	v_lshl_add_u64 v[2:3], s[56:57], 0, v[2:3]
	v_add_u32_e32 v146, s31, v5
	v_add_u32_e32 v147, s34, v5
	s_add_i32 s31, s31, s15
	s_add_i32 s34, s34, s15
	v_add_u32_e32 v149, s62, v5
	v_add_u32_e32 v150, s64, v5
	s_add_i32 s62, s62, s15
	s_add_i32 s64, s64, s15
	v_lshl_add_u64 v[140:141], v[2:3], 0, s[20:21]
	v_add_u32_e32 v148, 0, v4
	s_add_i32 s29, s2, 0xc000
	s_add_i32 s30, s2, 0xe000
	s_add_i32 s33, s31, 0x2000
	s_add_i32 s35, s34, 0x2000
	s_add_i32 s63, s62, 0x2000
	s_add_i32 s65, s64, 0x2000
	s_barrier
	s_branch .LBB0_381

.LBB0_394:
	s_add_u32 s25, s56, 0x9d00000
	s_addc_u32 s28, s57, 0
	s_lshl_b32 s14, s14, 5
	s_lshl_b32 s29, s15, 6
	s_lshl_b32 s22, s15, 13
	s_and_b32 s30, s14, 0x60
	s_add_u32 s14, s48, 0x1000
	s_addc_u32 s15, s49, 0
	s_add_i32 m0, s17, 0x18000
	v_lshl_add_u64 v[2:3], s[14:15], 0, v[134:135]
	global_load_lds_dwordx4 v[2:3], off
	s_add_i32 m0, s17, 0x1a000
	v_lshl_add_u64 v[2:3], s[14:15], 0, v[130:131]
	s_add_u32 s14, s56, 0x3580080
	s_addc_u32 s15, s57, 0
	s_add_i32 s31, s17, 0x8000
	global_load_lds_dwordx4 v[2:3], off
	v_lshl_add_u64 v[2:3], s[14:15], 0, v[136:137]
	s_mov_b32 m0, s31
	s_add_i32 s33, s17, 0xa000
	global_load_lds_dwordx4 v[2:3], off
	v_lshl_add_u64 v[2:3], s[14:15], 0, v[132:133]
	s_add_u32 s14, s48, 0x11000
	s_mov_b32 m0, s33
	s_addc_u32 s15, s49, 0
	global_load_lds_dwordx4 v[2:3], off
	s_add_i32 m0, s17, 0x1c000
	v_lshl_add_u64 v[2:3], s[14:15], 0, v[134:135]
	global_load_lds_dwordx4 v[2:3], off
	v_lshl_add_u64 v[2:3], s[14:15], 0, v[130:131]
	s_add_i32 m0, s17, 0x1e000
	s_cmpk_lt_u32 s12, 0x100
	global_load_lds_dwordx4 v[2:3], off
	s_waitcnt vmcnt(8)
	s_barrier
	v_lshlrev_b32_e32 v3, 2, v1
	v_lshl_or_b32 v2, v1, 6, v143
	v_and_b32_e32 v3, 32, v3
	v_bitop3_b32 v2, v2, s22, v3 bitop3:0xde
	s_cselect_b64 s[22:23], -1, 0
	s_cmpk_gt_i32 s94, 0x7f
	s_cselect_b64 s[14:15], -1, 0
	s_and_b32 s12, s94, 0xffffffc0
	s_waitcnt vmcnt(6)
	s_cmp_eq_u32 s12, 64
	v_lshl_or_b32 v140, s30, 7, v144
	s_cselect_b64 s[26:27], -1, 0
	s_add_i32 s62, 0, 0x10000
	s_add_i32 s63, 0, 0x14000
	s_add_i32 s34, s94, 0x100
	s_add_i32 s35, s94, 0x80
	v_add_u32_e32 v141, s62, v140
	v_add_u32_e32 v143, s63, v140
	v_add_u32_e32 v144, 0, v2
	s_mov_b64 s[36:37], 0x80
	s_xor_b64 s[38:39], s[14:15], -1
	s_mov_b32 s46, 0
	s_barrier
	s_branch .LBB0_397

.LBB0_471:
	s_lshl_b32 s8, s8, 5
	s_lshl_b32 s30, s9, 6
	s_lshl_b32 s11, s9, 13
	s_and_b32 s31, s8, 0x60
	s_mov_b64 s[8:9], 0x80
	s_add_i32 m0, s19, 0x18000
	v_lshl_add_u64 v[8:9], v[8:9], 0, s[8:9]
	s_lshl_b32 s20, s31, 7
	global_load_lds_dwordx4 v[8:9], off
	v_lshl_add_u64 v[6:7], v[6:7], 0, s[8:9]
	s_add_i32 m0, s19, 0x1a000
	s_add_i32 s33, s19, 0x8000
	s_add_i32 s34, s19, 0xa000
	global_load_lds_dwordx4 v[6:7], off
	v_lshl_add_u64 v[2:3], v[2:3], 0, s[8:9]
	s_mov_b32 m0, s33
	s_add_u32 s12, s38, 0x200080
	global_load_lds_dwordx4 v[2:3], off
	v_lshl_add_u64 v[2:3], v[4:5], 0, s[8:9]
	s_mov_b32 m0, s34
	s_addc_u32 s13, s39, 0
	global_load_lds_dwordx4 v[2:3], off
	s_add_i32 m0, s19, 0x1c000
	v_lshl_add_u64 v[2:3], s[12:13], 0, v[134:135]
	global_load_lds_dwordx4 v[2:3], off
	v_lshl_add_u64 v[2:3], s[12:13], 0, v[130:131]
	s_add_i32 m0, s19, 0x1e000
	v_bfe_u32 v142, v0, 4, 2
	global_load_lds_dwordx4 v[2:3], off
	s_waitcnt vmcnt(8)
	s_barrier
	v_and_b32_e32 v1, 15, v0
	v_lshlrev_b32_e32 v2, 4, v142
	v_lshlrev_b32_e32 v4, 2, v0
	v_lshl_or_b32 v3, v1, 6, v2
	v_and_b32_e32 v4, 32, v4
	v_bitop3_b32 v3, v3, s11, v4 bitop3:0xde
	v_lshlrev_b32_e32 v5, 6, v0
	s_movk_i32 s11, 0x3c0
	v_and_or_b32 v2, v5, s11, v2
	v_bitop3_b32 v143, s20, v2, v4 bitop3:0xf6
	v_lshlrev_b32_e32 v2, 7, v0
	s_waitcnt vmcnt(6)
	s_cmpk_lt_u32 s10, 0x100
	v_and_b32_e32 v2, 0xc000, v2
	v_lshlrev_b32_e32 v4, 10, v12
	s_cselect_b64 s[10:11], -1, 0
	v_or3_b32 v2, v10, v2, v4
	s_add_i32 s35, 0, 0x10000
	s_add_i32 s44, 0, 0x14000
	v_add_u32_e32 v138, v2, v11
	v_mov_b32_e32 v139, v135
	v_add3_u32 v140, v13, v10, v11
	v_mov_b32_e32 v141, v135
	v_add_u32_e32 v144, s35, v143
	v_add_u32_e32 v145, s44, v143
	v_add_u32_e32 v146, 0, v3
	s_mov_b32 s48, 0
	s_barrier
	s_branch .LBB0_474

.LBB0_552:
	v_bfe_u32 v188, v0, 4, 2
	s_add_u32 s91, s56, 0xc0000
	v_and_b32_e32 v1, 15, v0
	v_lshlrev_b32_e32 v14, 4, v188
	v_lshlrev_b32_e32 v16, 2, v0
	s_addc_u32 s92, s57, 0
	v_lshl_or_b32 v15, v1, 6, v14
	s_lshl_b32 s4, s10, 13
	v_and_b32_e32 v16, 32, v16
	v_bitop3_b32 v15, v15, s4, v16 bitop3:0xde
	s_lshl_b32 s4, s11, 5
	s_mov_b64 s[22:23], 0x80
	s_and_b32 s94, s4, 0x60
	v_lshlrev_b32_e32 v17, 6, v0
	s_movk_i32 s4, 0x3c0
	s_add_i32 m0, s87, 0x18000
	v_lshl_add_u64 v[8:9], v[8:9], 0, s[22:23]
	s_lshl_b32 s93, s10, 6
	v_and_or_b32 v14, v17, s4, v14
	s_lshl_b32 s4, s94, 7
	global_load_lds_dwordx4 v[8:9], off
	v_lshl_add_u64 v[6:7], v[6:7], 0, s[22:23]
	s_add_i32 m0, s87, 0x1a000
	s_add_i32 s95, s87, 0x8000
	s_add_i32 s96, s87, 0xa000
	v_bitop3_b32 v189, s4, v14, v16 bitop3:0xf6
	global_load_lds_dwordx4 v[6:7], off
	v_lshl_add_u64 v[2:3], v[2:3], 0, s[22:23]
	s_mov_b32 m0, s95
	s_add_u32 s4, s78, 0x40080
	global_load_lds_dwordx4 v[2:3], off
	v_lshl_add_u64 v[2:3], v[4:5], 0, s[22:23]
	s_mov_b32 m0, s96
	s_addc_u32 s5, s79, 0
	global_load_lds_dwordx4 v[2:3], off
	s_add_i32 m0, s87, 0x1c000
	v_lshl_add_u64 v[2:3], s[4:5], 0, v[172:173]
	global_load_lds_dwordx4 v[2:3], off
	v_lshl_add_u64 v[2:3], s[4:5], 0, v[176:177]
	s_add_i32 m0, s87, 0x1e000
	v_readlane_b32 s4, v249, 2
	s_cmpk_lt_u32 s2, 0x100
	v_readlane_b32 s5, v249, 3
	s_cselect_b64 s[26:27], -1, 0
	s_lshl_b32 s84, s10, 14
	s_ashr_i32 s97, s4, 31
	v_readlane_b32 s4, v249, 30
	s_add_i32 s84, s84, 0x7fff0000
	s_waitcnt lgkmcnt(0)
	s_ashr_i32 s42, s4, 31
	s_bitcmp0_b32 s4, 0
	s_mov_b32 s8, s4
	s_cselect_b64 s[36:37], -1, 0
	s_lshr_b32 s2, s42, 29
	v_readlane_b32 s5, v249, 31
	s_add_i32 s2, s4, s2
	s_ashr_i32 s43, s8, 2
	s_ashr_i32 s4, s2, 3
	s_and_b32 s2, s2, -8
	s_add_i32 s5, s43, 0x100
	s_sub_i32 s2, s8, s2
	s_and_b32 s44, s8, 2
	s_ashr_i32 s8, s5, 31
	s_lshr_b32 s8, s8, 29
	s_add_i32 s8, s5, s8
	s_ashr_i32 s16, s8, 3
	s_and_b32 s8, s8, -8
	s_sub_i32 s17, s5, s8
	s_lshl_b32 s24, s44, 9
	s_and_b32 s5, s1, 0xffff
	s_and_b32 s9, s55, 0xffff
	s_cmp_lt_i32 s2, 0
	global_load_lds_dwordx4 v[2:3], off
	s_waitcnt vmcnt(8)
	s_barrier
	s_cselect_b32 s8, 41, 40
	s_mul_i32 s2, s2, s8
	s_add_i32 s2, s2, s4
	s_ashr_i32 s4, s2, 31
	s_lshr_b32 s4, s4, 27
	s_add_i32 s4, s2, s4
	s_ashr_i32 s4, s4, 5
	s_lshl_b32 s18, s4, 3
	s_sub_i32 s8, 0x50, s18
	s_lshl_b32 s4, s4, 5
	s_min_i32 s19, s8, 8
	s_sub_i32 s2, s2, s4
	s_cmp_lt_i32 s17, 0
	s_cselect_b32 s25, 41, 40
	s_abs_i32 s28, s19
	v_cvt_f32_u32_e32 v2, s28
	s_mul_i32 s17, s17, s25
	s_add_i32 s16, s17, s16
	s_sub_i32 s33, 0, s28
	v_rcp_iflag_f32_e32 v2, v2
	s_ashr_i32 s17, s16, 31
	s_lshr_b32 s17, s17, 27
	s_add_i32 s17, s16, s17
	v_mul_f32_e32 v2, 0x4f7ffffe, v2
	v_cvt_u32_f32_e32 v2, v2
	s_abs_i32 s30, s2
	s_ashr_i32 s25, s17, 5
	s_lshl_b32 s25, s25, 3
	v_readfirstlane_b32 s34, v2
	s_mul_i32 s33, s33, s34
	s_mul_hi_u32 s33, s34, s33
	s_add_i32 s34, s34, s33
	s_mul_hi_u32 s33, s30, s34
	s_andn2_b32 s17, s17, 31
	s_mul_i32 s34, s33, s28
	s_sub_i32 s29, 0x50, s25
	s_sub_i32 s17, s16, s17
	s_xor_b32 s16, s2, s19
	s_sub_i32 s30, s30, s34
	s_min_i32 s29, s29, 8
	s_ashr_i32 s16, s16, 31
	s_add_i32 s34, s33, 1
	s_sub_i32 s38, s30, s28
	s_cmp_ge_u32 s30, s28
	s_cselect_b32 s33, s34, s33
	s_cselect_b32 s30, s38, s30
	s_add_i32 s34, s33, 1
	s_cmp_ge_u32 s30, s28
	s_cselect_b32 s28, s34, s33
	s_xor_b32 s28, s28, s16
	s_sub_i32 s38, s28, s16
	s_mul_i32 s16, s38, s19
	s_sub_i32 s2, s2, s16
	s_add_i32 s16, s18, s2
	s_abs_i32 s2, s29
	v_cvt_f32_u32_e32 v2, s2
	s_lshl_b32 s18, s16, 8
	s_ashr_i32 s19, s18, 31
	s_lshl_b64 s[18:19], s[18:19], 11
	v_rcp_iflag_f32_e32 v2, v2
	v_writelane_b32 v249, s18, 32
	s_ashr_i32 s39, s38, 31
	s_sub_i32 s28, 0, s2
	v_mul_f32_e32 v2, 0x4f7ffffe, v2
	v_cvt_u32_f32_e32 v2, v2
	v_writelane_b32 v249, s19, 33
	s_lshl_b64 s[18:19], s[38:39], 19
	v_writelane_b32 v249, s18, 34
	v_readfirstlane_b32 s30, v2
	s_mul_i32 s28, s28, s30
	s_mul_hi_u32 s28, s30, s28
	v_writelane_b32 v249, s19, 35
	s_abs_i32 s19, s17
	s_add_i32 s30, s30, s28
	s_mul_hi_u32 s28, s19, s30
	s_mul_i32 s30, s28, s2
	s_xor_b32 s18, s17, s29
	s_sub_i32 s19, s19, s30
	s_ashr_i32 s18, s18, 31
	s_add_i32 s30, s28, 1
	s_sub_i32 s33, s19, s2
	s_cmp_ge_u32 s19, s2
	s_cselect_b32 s28, s30, s28
	s_cselect_b32 s19, s33, s19
	s_add_i32 s30, s28, 1
	s_cmp_ge_u32 s19, s2
	s_cselect_b32 s2, s30, s28
	s_xor_b32 s2, s2, s18
	s_sub_i32 s46, s2, s18
	s_mul_i32 s2, s46, s29
	s_sub_i32 s2, s17, s2
	s_add_i32 s17, s25, s2
	s_lshl_b32 s18, s17, 8
	s_ashr_i32 s19, s18, 31
	s_ashr_i32 s47, s46, 31
	v_lshlrev_b32_e32 v2, 8, v0
	s_waitcnt vmcnt(6)
	s_lshl_b64 s[48:49], s[18:19], 11
	s_lshl_b64 s[64:65], s[46:47], 19
	v_and_b32_e32 v2, 0x18000, v2
	v_lshlrev_b32_e32 v3, 11, v12
	s_or_b32 s48, s48, s24
	s_or_b32 s64, s64, s24
	v_or3_b32 v2, v10, v2, v3
	s_add_i32 s24, 0, 0x10000
	s_add_i32 s25, 0, 0x14000
	s_mov_b32 s11, 0x20000
	s_brev_b32 s10, -2
	s_mov_b32 s4, s0
	s_mov_b32 s8, s54
	v_add_u32_e32 v180, v2, v11
	v_mov_b32_e32 v181, v179
	v_add3_u32 v182, v13, v10, v11
	v_mov_b32_e32 v183, v179
	v_add_u32_e32 v190, s24, v189
	v_add_u32_e32 v191, s25, v189
	v_add_u32_e32 v192, 0, v15
	v_mov_b64_e32 v[184:185], 0x13f
	s_barrier
	s_branch .LBB0_555

.LBB0_739:
	s_lshl_b32 s10, s10, 5
	s_lshl_b32 s30, s11, 6
	s_lshl_b32 s14, s11, 13
	s_and_b32 s31, s10, 0x60
	s_mov_b64 s[10:11], 0x80
	s_add_i32 m0, s19, 0x18000
	v_lshl_add_u64 v[8:9], v[8:9], 0, s[10:11]
	s_lshl_b32 s15, s31, 7
	global_load_lds_dwordx4 v[8:9], off
	v_lshl_add_u64 v[6:7], v[6:7], 0, s[10:11]
	s_add_i32 m0, s19, 0x1a000
	s_add_i32 s33, s19, 0x8000
	s_add_i32 s35, s19, 0xa000
	global_load_lds_dwordx4 v[6:7], off
	v_lshl_add_u64 v[2:3], v[2:3], 0, s[10:11]
	s_mov_b32 m0, s33
	s_add_u32 s12, s44, 0x40080
	global_load_lds_dwordx4 v[2:3], off
	v_lshl_add_u64 v[2:3], v[4:5], 0, s[10:11]
	s_mov_b32 m0, s35
	s_addc_u32 s13, s45, 0
	global_load_lds_dwordx4 v[2:3], off
	s_add_i32 m0, s19, 0x1c000
	v_lshl_add_u64 v[2:3], s[12:13], 0, v[134:135]
	global_load_lds_dwordx4 v[2:3], off
	v_lshl_add_u64 v[2:3], s[12:13], 0, v[130:131]
	s_add_i32 m0, s19, 0x1e000
	v_bfe_u32 v148, v0, 4, 2
	global_load_lds_dwordx4 v[2:3], off
	s_waitcnt vmcnt(8)
	s_barrier
	s_sext_i32_i8 s64, s4
	v_and_b32_e32 v1, 15, v0
	v_lshlrev_b32_e32 v2, 4, v148
	v_lshlrev_b32_e32 v4, 2, v0
	v_lshlrev_b32_e32 v5, 6, v0
	s_movk_i32 s4, 0x3c0
	v_lshl_or_b32 v3, v1, 6, v2
	v_and_b32_e32 v4, 32, v4
	v_and_or_b32 v2, v5, s4, v2
	v_bitop3_b32 v149, s15, v2, v4 bitop3:0xf6
	v_lshlrev_b32_e32 v2, 8, v0
	v_bitop3_b32 v3, v3, s14, v4 bitop3:0xde
	s_waitcnt vmcnt(6)
	s_cmpk_lt_u32 s5, 0x100
	v_and_b32_e32 v2, 0x18000, v2
	v_lshlrev_b32_e32 v4, 11, v12
	s_cselect_b64 s[12:13], -1, 0
	v_readlane_b32 s4, v249, 2
	v_or3_b32 v2, v10, v2, v4
	s_add_i32 s49, 0, 0x10000
	s_add_i32 s62, 0, 0x14000
	s_ashr_i32 s48, s4, 31
	v_add_u32_e32 v138, v2, v11
	v_mov_b32_e32 v139, v135
	v_add3_u32 v140, v13, v10, v11
	v_mov_b32_e32 v141, v135
	v_mov_b64_e32 v[142:143], 0x500
	v_mov_b64_e32 v[144:145], 0x4ff
	v_add_u32_e32 v150, s49, v149
	v_add_u32_e32 v151, s62, v149
	v_add_u32_e32 v152, 0, v3
	s_barrier
	v_readlane_b32 s5, v249, 3
	s_waitcnt vmcnt(0)
	s_branch .LBB0_742

.LBB0_820:
	s_add_u32 s4, s56, 0x3500000
	s_addc_u32 s5, s57, 0
	v_bfe_u32 v188, v0, 4, 2
	s_add_u32 s91, s56, 0xc5000
	v_and_b32_e32 v1, 15, v0
	v_lshlrev_b32_e32 v14, 4, v188
	v_lshlrev_b32_e32 v16, 2, v0
	s_addc_u32 s92, s57, 0
	v_lshl_or_b32 v15, v1, 6, v14
	s_lshl_b32 s8, s10, 13
	v_and_b32_e32 v16, 32, v16
	v_bitop3_b32 v15, v15, s8, v16 bitop3:0xde
	s_lshl_b32 s8, s11, 5
	s_mov_b64 s[22:23], 0x80
	s_and_b32 s94, s8, 0x60
	v_lshlrev_b32_e32 v17, 6, v0
	s_movk_i32 s8, 0x3c0
	s_add_i32 m0, s87, 0x18000
	v_lshl_add_u64 v[8:9], v[8:9], 0, s[22:23]
	s_lshl_b32 s93, s10, 6
	v_and_or_b32 v14, v17, s8, v14
	s_lshl_b32 s8, s94, 7
	global_load_lds_dwordx4 v[8:9], off
	v_lshl_add_u64 v[6:7], v[6:7], 0, s[22:23]
	s_add_i32 m0, s87, 0x1a000
	s_add_i32 s95, s87, 0x8000
	s_add_i32 s96, s87, 0xa000
	v_bitop3_b32 v189, s8, v14, v16 bitop3:0xf6
	global_load_lds_dwordx4 v[6:7], off
	v_lshl_add_u64 v[2:3], v[2:3], 0, s[22:23]
	s_mov_b32 m0, s95
	s_add_u32 s8, s78, 0x100080
	global_load_lds_dwordx4 v[2:3], off
	v_lshl_add_u64 v[2:3], v[4:5], 0, s[22:23]
	s_mov_b32 m0, s96
	s_addc_u32 s9, s79, 0
	global_load_lds_dwordx4 v[2:3], off
	s_add_i32 m0, s87, 0x1c000
	v_lshl_add_u64 v[2:3], s[8:9], 0, v[172:173]
	global_load_lds_dwordx4 v[2:3], off
	v_lshl_add_u64 v[2:3], s[8:9], 0, v[176:177]
	s_add_i32 m0, s87, 0x1e000
	v_readlane_b32 s8, v249, 2
	s_cmpk_lt_u32 s15, 0x100
	v_readlane_b32 s9, v249, 3
	s_cselect_b64 s[26:27], -1, 0
	s_lshl_b32 s97, s10, 14
	s_ashr_i32 s84, s8, 31
	v_readlane_b32 s8, v249, 30
	s_add_i32 s97, s97, 0x7fff0000
	s_waitcnt lgkmcnt(0)
	s_ashr_i32 s42, s8, 31
	s_mov_b32 s16, s8
	s_bitcmp0_b32 s8, 0
	v_readlane_b32 s9, v249, 31
	s_cselect_b64 s[36:37], -1, 0
	s_ashr_i32 s43, s16, 2
	s_add_i32 s9, s43, 0x100
	s_ashr_i32 s11, s9, 31
	s_lshr_b32 s8, s42, 29
	s_lshr_b32 s11, s11, 29
	s_add_i32 s8, s16, s8
	s_add_i32 s11, s9, s11
	s_ashr_i32 s10, s8, 3
	s_and_b32 s8, s8, -8
	s_and_b32 s44, s16, 2
	s_ashr_i32 s15, s11, 3
	s_and_b32 s11, s11, -8
	s_sub_i32 s8, s16, s8
	s_sub_i32 s16, s9, s11
	s_lshl_b32 s24, s44, 11
	s_and_b32 s5, s5, 0xffff
	s_and_b32 s9, s55, 0xffff
	s_cmp_lt_i32 s8, 0
	global_load_lds_dwordx4 v[2:3], off
	s_waitcnt vmcnt(8)
	s_barrier
	s_cselect_b32 s11, 41, 40
	s_mul_i32 s8, s8, s11
	s_add_i32 s8, s8, s10
	s_ashr_i32 s10, s8, 31
	s_lshr_b32 s10, s10, 27
	s_add_i32 s10, s8, s10
	s_ashr_i32 s10, s10, 5
	s_lshl_b32 s17, s10, 3
	s_sub_i32 s11, 0x50, s17
	s_lshl_b32 s10, s10, 5
	s_min_i32 s18, s11, 8
	s_sub_i32 s19, s8, s10
	s_cmp_lt_i32 s16, 0
	s_cselect_b32 s25, 41, 40
	s_abs_i32 s28, s18
	v_cvt_f32_u32_e32 v2, s28
	s_mul_i32 s16, s16, s25
	s_add_i32 s15, s16, s15
	s_sub_i32 s31, 0, s28
	v_rcp_iflag_f32_e32 v2, v2
	s_ashr_i32 s16, s15, 31
	s_lshr_b32 s16, s16, 27
	s_add_i32 s16, s15, s16
	v_mul_f32_e32 v2, 0x4f7ffffe, v2
	v_cvt_u32_f32_e32 v2, v2
	s_abs_i32 s30, s19
	s_ashr_i32 s25, s16, 5
	s_lshl_b32 s25, s25, 3
	v_readfirstlane_b32 s34, v2
	s_mul_i32 s31, s31, s34
	s_mul_hi_u32 s31, s34, s31
	s_add_i32 s34, s34, s31
	s_mul_hi_u32 s31, s30, s34
	s_andn2_b32 s16, s16, 31
	s_mul_i32 s34, s31, s28
	s_sub_i32 s29, 0x50, s25
	s_sub_i32 s15, s15, s16
	s_xor_b32 s16, s19, s18
	s_sub_i32 s30, s30, s34
	s_min_i32 s29, s29, 8
	s_ashr_i32 s16, s16, 31
	s_add_i32 s34, s31, 1
	s_sub_i32 s38, s30, s28
	s_cmp_ge_u32 s30, s28
	s_cselect_b32 s31, s34, s31
	s_cselect_b32 s30, s38, s30
	s_add_i32 s34, s31, 1
	s_cmp_ge_u32 s30, s28
	s_cselect_b32 s28, s34, s31
	s_xor_b32 s28, s28, s16
	s_sub_i32 s38, s28, s16
	s_mul_i32 s16, s38, s18
	s_sub_i32 s16, s19, s16
	s_add_i32 s16, s17, s16
	s_abs_i32 s17, s29
	v_cvt_f32_u32_e32 v2, s17
	s_lshl_b32 s18, s16, 8
	s_ashr_i32 s19, s18, 31
	s_lshl_b64 s[18:19], s[18:19], 13
	v_rcp_iflag_f32_e32 v2, v2
	v_writelane_b32 v249, s18, 32
	s_ashr_i32 s39, s38, 31
	s_sub_i32 s28, 0, s17
	v_mul_f32_e32 v2, 0x4f7ffffe, v2
	v_cvt_u32_f32_e32 v2, v2
	v_writelane_b32 v249, s19, 33
	s_lshl_b64 s[18:19], s[38:39], 21
	v_writelane_b32 v249, s18, 34
	v_readfirstlane_b32 s30, v2
	s_mul_i32 s28, s28, s30
	s_mul_hi_u32 s28, s30, s28
	v_writelane_b32 v249, s19, 35
	s_abs_i32 s19, s15
	s_add_i32 s30, s30, s28
	s_mul_hi_u32 s28, s19, s30
	s_mul_i32 s30, s28, s17
	s_xor_b32 s18, s15, s29
	s_sub_i32 s19, s19, s30
	s_ashr_i32 s18, s18, 31
	s_add_i32 s30, s28, 1
	s_sub_i32 s31, s19, s17
	s_cmp_ge_u32 s19, s17
	s_cselect_b32 s28, s30, s28
	s_cselect_b32 s19, s31, s19
	s_add_i32 s30, s28, 1
	s_cmp_ge_u32 s19, s17
	s_cselect_b32 s17, s30, s28
	s_xor_b32 s17, s17, s18
	s_sub_i32 s46, s17, s18
	s_mul_i32 s17, s46, s29
	s_sub_i32 s15, s15, s17
	s_add_i32 s17, s25, s15
	s_lshl_b32 s18, s17, 8
	s_ashr_i32 s19, s18, 31
	s_ashr_i32 s47, s46, 31
	v_lshlrev_b32_e32 v2, 10, v0
	s_waitcnt vmcnt(6)
	s_lshl_b64 s[48:49], s[18:19], 13
	s_lshl_b64 s[64:65], s[46:47], 21
	v_and_b32_e32 v2, 0x60000, v2
	v_lshlrev_b32_e32 v3, 13, v12
	s_or_b32 s48, s48, s24
	s_or_b32 s64, s64, s24
	v_or3_b32 v2, v10, v2, v3
	s_add_i32 s24, 0, 0x10000
	s_add_i32 s25, 0, 0x14000
	s_mov_b32 s11, 0x20000
	s_brev_b32 s10, -2
	s_mov_b32 s8, s54
	v_add_u32_e32 v180, v2, v11
	v_mov_b32_e32 v181, v179
	v_add3_u32 v182, v13, v10, v11
	v_mov_b32_e32 v183, v179
	v_add_u32_e32 v190, s24, v189
	v_add_u32_e32 v191, s25, v189
	v_add_u32_e32 v192, 0, v15
	v_mov_b64_e32 v[184:185], 0x13f
	s_barrier
	s_branch .LBB0_823

.LBB0_1007:
	s_add_u32 s10, s56, 0x3500000
	s_addc_u32 s11, s57, 0
	s_add_u32 s12, s56, 0x5d00000
	s_addc_u32 s13, s57, 0
	s_add_u32 s20, s56, 0x8500000
	s_addc_u32 s21, s57, 0
	s_add_u32 s22, s56, 0xad00000
	s_addc_u32 s23, s57, 0
	s_add_u32 s26, s56, 0xd500000
	s_addc_u32 s27, s57, 0
	s_lshl_b32 s6, s6, 5
	s_waitcnt lgkmcnt(0)
	s_mov_b64 s[36:37], 0x80
	s_and_b32 s78, s6, 0x60
	s_add_i32 m0, s73, 0x18000
	v_lshl_add_u64 v[8:9], v[8:9], 0, s[36:37]
	s_lshl_b32 s77, s14, 6
	s_lshl_b32 s17, s14, 13
	s_lshl_b32 s6, s78, 7
	global_load_lds_dwordx4 v[8:9], off
	v_lshl_add_u64 v[6:7], v[6:7], 0, s[36:37]
	s_add_i32 m0, s73, 0x1a000
	s_add_i32 s79, s73, 0x8000
	s_add_i32 s80, s73, 0xa000
	global_load_lds_dwordx4 v[6:7], off
	v_lshl_add_u64 v[2:3], v[2:3], 0, s[36:37]
	s_mov_b32 m0, s79
	s_add_u32 s14, s66, 0x40080
	global_load_lds_dwordx4 v[2:3], off
	v_lshl_add_u64 v[2:3], v[4:5], 0, s[36:37]
	s_mov_b32 m0, s80
	s_addc_u32 s15, s67, 0
	global_load_lds_dwordx4 v[2:3], off
	s_add_i32 m0, s73, 0x1c000
	v_lshl_add_u64 v[2:3], s[14:15], 0, v[150:151]
	global_load_lds_dwordx4 v[2:3], off
	v_lshl_add_u64 v[2:3], s[14:15], 0, v[146:147]
	s_add_i32 m0, s73, 0x1e000
	v_bfe_u32 v170, v0, 4, 2
	global_load_lds_dwordx4 v[2:3], off
	s_waitcnt vmcnt(8)
	s_barrier
	s_sext_i32_i16 s16, s4
	v_and_b32_e32 v1, 15, v0
	v_lshlrev_b32_e32 v3, 4, v170
	v_lshlrev_b32_e32 v5, 2, v0
	v_lshlrev_b32_e32 v6, 6, v0
	s_movk_i32 s4, 0x3c0
	v_lshl_or_b32 v4, v1, 6, v3
	v_and_b32_e32 v5, 32, v5
	v_and_or_b32 v3, v6, s4, v3
	v_bitop3_b32 v171, s6, v3, v5 bitop3:0xf6
	v_lshlrev_b32_e32 v3, 8, v0
	v_bitop3_b32 v4, v4, s17, v5 bitop3:0xde
	s_waitcnt vmcnt(6)
	s_cmpk_lt_u32 s5, 0x100
	v_and_b32_e32 v3, 0x18000, v3
	v_lshlrev_b32_e32 v5, 11, v12
	v_lshlrev_b32_e32 v2, 3, v170
	s_cselect_b64 s[38:39], -1, 0
	v_readlane_b32 s4, v249, 2
	v_or3_b32 v3, v10, v3, v5
	s_add_i32 s82, 0, 0x10000
	s_add_i32 s83, 0, 0x14000
	s_ashr_i32 s81, s4, 31
	v_add_u32_e32 v156, v3, v11
	v_mov_b32_e32 v157, v155
	v_add3_u32 v158, v13, v10, v11
	v_mov_b32_e32 v159, v155
	v_mov_b64_e32 v[160:161], 0x640
	v_mov_b64_e32 v[162:163], 0x63f
	v_add_u32_e32 v172, s82, v171
	v_add_u32_e32 v173, s83, v171
	v_add_u32_e32 v174, 0, v4
	s_lshl_b32 s85, s78, 2
	v_lshlrev_b32_e32 v154, 2, v2
	s_mov_b32 s86, 0x4f000
	s_mov_b32 s87, 0
	s_barrier
	v_readlane_b32 s5, v249, 3
	s_branch .LBB0_1010

.LBB0_1414:
	v_lshlrev_b32_e32 v11, 2, v206
	s_lshl_b32 s12, s12, 5
	s_add_i32 m0, s28, 0x18000
	v_lshl_add_u64 v[2:3], v[2:3], 0, s[76:77]
	s_lshl_b32 s46, s6, 6
	v_lshl_or_b32 v10, v206, 6, v208
	s_lshl_b32 s14, s6, 13
	v_and_b32_e32 v11, 32, v11
	s_and_b32 s47, s12, 0x60
	global_load_lds_dwordx4 v[2:3], off
	v_lshl_add_u64 v[2:3], v[4:5], 0, s[76:77]
	s_add_i32 m0, s28, 0x1a000
	s_add_i32 s44, s28, 0x8000
	s_add_i32 s36, s28, 0xa000
	v_bitop3_b32 v10, v10, s14, v11 bitop3:0xde
	global_load_lds_dwordx4 v[2:3], off
	v_lshl_add_u64 v[2:3], v[8:9], 0, s[76:77]
	s_mov_b32 m0, s44
	s_add_u32 s14, s94, 0x40080
	global_load_lds_dwordx4 v[2:3], off
	v_lshl_add_u64 v[2:3], v[6:7], 0, s[76:77]
	s_mov_b32 m0, s36
	s_addc_u32 s15, s95, 0
	global_load_lds_dwordx4 v[2:3], off
	s_add_i32 m0, s28, 0x1c000
	v_lshl_add_u64 v[2:3], s[14:15], 0, v[174:175]
	global_load_lds_dwordx4 v[2:3], off
	v_lshl_add_u64 v[2:3], s[14:15], 0, v[178:179]
	s_add_i32 m0, s28, 0x1e000
	s_cmpk_lt_u32 s2, 0x100
	global_load_lds_dwordx4 v[2:3], off
	s_waitcnt vmcnt(8)
	s_barrier
	s_waitcnt vmcnt(6)
	s_cselect_b64 s[82:83], -1, 0
	s_lshl_b32 s37, s6, 14
	v_lshl_or_b32 v199, s47, 7, v209
	s_add_i32 s37, s37, 0x7fff0000
	s_mov_b32 s51, 0
	v_add_u32_e32 v214, 0, v10
	s_barrier
	s_branch .LBB0_1417

.LBB0_1613:
	s_lshl_b32 s8, s8, 5
	s_lshl_b32 s40, s9, 6
	s_lshl_b32 s14, s9, 13
	s_and_b32 s41, s8, 0x60
	s_mov_b64 s[8:9], 0x80
	s_add_i32 m0, s19, 0x18000
	v_lshl_add_u64 v[8:9], v[8:9], 0, s[8:9]
	s_lshl_b32 s15, s41, 7
	global_load_lds_dwordx4 v[8:9], off
	v_lshl_add_u64 v[6:7], v[6:7], 0, s[8:9]
	s_add_i32 m0, s19, 0x1a000
	s_add_i32 s42, s19, 0x8000
	s_add_i32 s43, s19, 0xa000
	global_load_lds_dwordx4 v[6:7], off
	v_lshl_add_u64 v[2:3], v[2:3], 0, s[8:9]
	s_mov_b32 m0, s42
	s_add_u32 s10, s30, 0x40080
	global_load_lds_dwordx4 v[2:3], off
	v_lshl_add_u64 v[2:3], v[4:5], 0, s[8:9]
	s_mov_b32 m0, s43
	s_addc_u32 s11, s31, 0
	global_load_lds_dwordx4 v[2:3], off
	s_add_i32 m0, s19, 0x1c000
	v_lshl_add_u64 v[2:3], s[10:11], 0, v[134:135]
	global_load_lds_dwordx4 v[2:3], off
	v_lshl_add_u64 v[2:3], s[10:11], 0, v[130:131]
	s_add_i32 m0, s19, 0x1e000
	v_bfe_u32 v148, v0, 4, 2
	global_load_lds_dwordx4 v[2:3], off
	s_waitcnt vmcnt(8)
	s_barrier
	s_sext_i32_i8 s48, s4
	v_and_b32_e32 v1, 15, v0
	v_lshlrev_b32_e32 v2, 4, v148
	v_lshlrev_b32_e32 v4, 2, v0
	v_lshlrev_b32_e32 v5, 6, v0
	s_movk_i32 s4, 0x3c0
	v_lshl_or_b32 v3, v1, 6, v2
	v_and_b32_e32 v4, 32, v4
	v_and_or_b32 v2, v5, s4, v2
	v_bitop3_b32 v149, s15, v2, v4 bitop3:0xf6
	v_lshlrev_b32_e32 v2, 8, v0
	v_bitop3_b32 v3, v3, s14, v4 bitop3:0xde
	s_waitcnt vmcnt(6)
	s_cmpk_lt_u32 s5, 0x100
	v_and_b32_e32 v2, 0x18000, v2
	v_lshlrev_b32_e32 v4, 11, v12
	s_cselect_b64 s[10:11], -1, 0
	v_readlane_b32 s4, v249, 2
	v_or3_b32 v2, v10, v2, v4
	s_add_i32 s45, 0, 0x10000
	s_add_i32 s46, 0, 0x14000
	s_ashr_i32 s44, s4, 31
	v_add_u32_e32 v138, v2, v11
	v_mov_b32_e32 v139, v135
	v_add3_u32 v140, v13, v10, v11
	v_mov_b32_e32 v141, v135
	v_mov_b64_e32 v[142:143], 0x500
	v_mov_b64_e32 v[144:145], 0x4ff
	v_add_u32_e32 v150, s45, v149
	v_add_u32_e32 v151, s46, v149
	v_add_u32_e32 v152, 0, v3
	s_barrier
	v_readlane_b32 s5, v249, 3
	s_branch .LBB0_1616

.LBB0_1694:
	v_bfe_u32 v166, v0, 4, 2
	s_add_u32 s33, s56, 0xcf000
	v_and_b32_e32 v1, 15, v0
	v_lshlrev_b32_e32 v14, 4, v166
	v_lshlrev_b32_e32 v16, 2, v0
	s_addc_u32 s71, s57, 0
	v_lshl_or_b32 v15, v1, 6, v14
	s_lshl_b32 s4, s10, 13
	v_and_b32_e32 v16, 32, v16
	v_bitop3_b32 v15, v15, s4, v16 bitop3:0xde
	s_lshl_b32 s4, s11, 5
	s_mov_b64 s[16:17], 0x80
	s_and_b32 s73, s4, 0x60
	v_lshlrev_b32_e32 v17, 6, v0
	s_movk_i32 s4, 0x3c0
	s_add_i32 m0, s12, 0x18000
	v_lshl_add_u64 v[8:9], v[8:9], 0, s[16:17]
	s_lshl_b32 s72, s10, 6
	v_and_or_b32 v14, v17, s4, v14
	s_lshl_b32 s4, s73, 7
	global_load_lds_dwordx4 v[8:9], off
	v_lshl_add_u64 v[6:7], v[6:7], 0, s[16:17]
	s_add_i32 m0, s12, 0x1a000
	s_add_i32 s74, s12, 0x8000
	s_add_i32 s75, s12, 0xa000
	v_bitop3_b32 v167, s4, v14, v16 bitop3:0xf6
	global_load_lds_dwordx4 v[6:7], off
	v_lshl_add_u64 v[2:3], v[2:3], 0, s[16:17]
	s_mov_b32 m0, s74
	s_add_u32 s4, s62, 0x100080
	global_load_lds_dwordx4 v[2:3], off
	v_lshl_add_u64 v[2:3], v[4:5], 0, s[16:17]
	s_mov_b32 m0, s75
	s_addc_u32 s5, s63, 0
	global_load_lds_dwordx4 v[2:3], off
	s_add_i32 m0, s12, 0x1c000
	v_lshl_add_u64 v[2:3], s[4:5], 0, v[148:149]
	global_load_lds_dwordx4 v[2:3], off
	s_add_i32 m0, s12, 0x1e000
	s_cmpk_lt_u32 s20, 0x100
	v_lshl_add_u64 v[2:3], s[4:5], 0, v[152:153]
	s_cselect_b64 s[20:21], -1, 0
	s_lshl_b32 s76, s10, 14
	v_readlane_b32 s4, v249, 2
	s_add_i32 s76, s76, 0x7fff0000
	s_ashr_i32 s77, s4, 31
	s_ashr_i32 s78, s94, 31
	s_bitcmp0_b32 s94, 0
	v_readlane_b32 s5, v249, 3
	s_cselect_b64 s[22:23], -1, 0
	s_ashr_i32 s79, s94, 2
	s_add_i32 s5, s79, 0x100
	global_load_lds_dwordx4 v[2:3], off
	s_waitcnt vmcnt(8)
	s_barrier
	s_ashr_i32 s9, s5, 31
	s_lshr_b32 s4, s78, 29
	s_lshr_b32 s9, s9, 29
	s_add_i32 s4, s94, s4
	s_add_i32 s9, s5, s9
	v_readlane_b32 s28, v249, 27
	s_ashr_i32 s8, s4, 3
	s_and_b32 s4, s4, -8
	s_and_b32 s80, s94, 2
	s_ashr_i32 s24, s9, 3
	s_and_b32 s9, s9, -8
	v_readlane_b32 s29, v249, 28
	s_sub_i32 s4, s94, s4
	s_sub_i32 s25, s5, s9
	s_lshl_b32 s40, s80, 11
	s_and_b32 s5, s29, 0xffff
	s_and_b32 s9, s55, 0xffff
	s_cmp_lt_i32 s4, 0
	s_cselect_b32 s10, 41, 40
	s_mul_i32 s4, s4, s10
	s_add_i32 s4, s4, s8
	s_ashr_i32 s8, s4, 31
	s_lshr_b32 s8, s8, 27
	s_add_i32 s8, s4, s8
	s_ashr_i32 s10, s8, 5
	s_lshl_b32 s81, s10, 3
	s_sub_i32 s10, 0x50, s81
	s_andn2_b32 s8, s8, 31
	s_min_i32 s26, s10, 8
	s_sub_i32 s27, s4, s8
	s_cmp_lt_i32 s25, 0
	s_mov_b32 s4, s28
	s_cselect_b32 s28, 41, 40
	s_abs_i32 s29, s26
	v_cvt_f32_u32_e32 v2, s29
	s_mul_i32 s25, s25, s28
	s_add_i32 s24, s25, s24
	s_ashr_i32 s25, s24, 31
	v_rcp_iflag_f32_e32 v2, v2
	s_lshr_b32 s25, s25, 27
	s_add_i32 s25, s24, s25
	s_ashr_i32 s28, s25, 5
	v_mul_f32_e32 v2, 0x4f7ffffe, v2
	v_cvt_u32_f32_e32 v2, v2
	s_lshl_b32 s31, s28, 3
	s_sub_i32 s28, 0x50, s31
	s_min_i32 s36, s28, 8
	s_sub_i32 s28, 0, s29
	v_readfirstlane_b32 s30, v2
	s_mul_i32 s28, s28, s30
	s_andn2_b32 s25, s25, 31
	s_mul_hi_u32 s28, s30, s28
	s_sub_i32 s37, s24, s25
	s_abs_i32 s25, s27
	s_add_i32 s30, s30, s28
	s_mul_hi_u32 s28, s25, s30
	s_mul_i32 s30, s28, s29
	s_xor_b32 s24, s27, s26
	s_sub_i32 s25, s25, s30
	s_ashr_i32 s24, s24, 31
	s_add_i32 s30, s28, 1
	s_sub_i32 s38, s25, s29
	s_cmp_ge_u32 s25, s29
	s_cselect_b32 s28, s30, s28
	s_cselect_b32 s25, s38, s25
	s_add_i32 s30, s28, 1
	s_cmp_ge_u32 s25, s29
	s_cselect_b32 s25, s30, s28
	s_abs_i32 s30, s36
	v_cvt_f32_u32_e32 v2, s30
	s_xor_b32 s25, s25, s24
	s_sub_i32 s39, 0, s30
	s_sub_i32 s24, s25, s24
	v_rcp_iflag_f32_e32 v2, v2
	s_mul_i32 s25, s24, s26
	s_sub_i32 s25, s27, s25
	s_abs_i32 s38, s37
	v_mul_f32_e32 v2, 0x4f7ffffe, v2
	v_cvt_u32_f32_e32 v2, v2
	s_add_i32 s81, s81, s25
	s_lshl_b32 s26, s81, 8
	s_ashr_i32 s25, s24, 31
	v_readfirstlane_b32 s41, v2
	s_mul_i32 s39, s39, s41
	s_mul_hi_u32 s39, s41, s39
	s_add_i32 s41, s41, s39
	s_mul_hi_u32 s39, s38, s41
	s_mul_i32 s41, s39, s30
	s_ashr_i32 s27, s26, 31
	s_lshl_b64 s[28:29], s[24:25], 21
	s_xor_b32 s25, s37, s36
	s_sub_i32 s38, s38, s41
	s_lshl_b64 s[26:27], s[26:27], 13
	s_ashr_i32 s25, s25, 31
	s_add_i32 s41, s39, 1
	s_sub_i32 s42, s38, s30
	s_cmp_ge_u32 s38, s30
	s_cselect_b32 s39, s41, s39
	s_cselect_b32 s38, s42, s38
	s_add_i32 s41, s39, 1
	s_cmp_ge_u32 s38, s30
	s_cselect_b32 s30, s41, s39
	s_xor_b32 s30, s30, s25
	s_sub_i32 s30, s30, s25
	s_mul_i32 s25, s30, s36
	s_sub_i32 s25, s37, s25
	s_add_i32 s25, s31, s25
	s_lshl_b32 s36, s25, 8
	v_lshlrev_b32_e32 v2, 10, v0
	s_waitcnt vmcnt(6)
	s_ashr_i32 s37, s36, 31
	s_ashr_i32 s31, s30, 31
	v_and_b32_e32 v2, 0x60000, v2
	v_lshlrev_b32_e32 v3, 13, v12
	s_lshl_b64 s[36:37], s[36:37], 13
	s_lshl_b64 s[38:39], s[30:31], 21
	v_or3_b32 v2, v10, v2, v3
	s_add_i32 s31, 0, 0x10000
	s_add_i32 s82, 0, 0x14000
	s_mov_b32 s11, 0x20000
	s_brev_b32 s10, -2
	s_mov_b32 s8, s54
	s_or_b32 s36, s36, s40
	s_or_b32 s38, s38, s40
	v_add_u32_e32 v156, v2, v11
	v_mov_b32_e32 v157, v155
	v_add3_u32 v158, v13, v10, v11
	v_mov_b32_e32 v159, v155
	v_add_u32_e32 v168, s31, v167
	v_add_u32_e32 v169, s82, v167
	v_add_u32_e32 v170, 0, v15
	v_mov_b64_e32 v[160:161], 0x13f
	s_barrier
	s_branch .LBB0_1697
